# v106 + G4 epilogue row-sum butterflies via permlane16/32_swap instead of serial ds_bpermute
# speedup vs baseline: 1.0050x; 1.0050x over previous
.LBB0_1145:
	s_lshl_b32 s5, s8, 8
	v_mbcnt_lo_u32_b32 v128, -1, 0
	v_mbcnt_hi_u32_b32 v128, -1, v128
	v_mbcnt_lo_u32_b32 v199, -1, 0
	v_mbcnt_hi_u32_b32 v199, -1, v199
	s_add_i32 s5, s5, s54
	v_and_b32_e32 v239, 15, v199
	v_or_b32_e32 v128, s5, v239
	s_lshl_b32 s9, s4, 9
	s_or_b32 s9, s9, s59
	v_and_b32_e32 v240, -16, v199
	v_lshlrev_b32_e32 v128, 11, v128
	v_add3_u32 v192, s9, v240, v128
	v_add_u32_e32 v128, s5, v240
	v_or_b32_e32 v128, v128, v239
	v_ashrrev_i32_e32 v129, 31, v128
	v_lshl_add_u64 v[130:131], v[128:129], 2, s[22:23]
	global_load_dword v205, v[130:131], off
	global_load_dwordx4 v[242:245], v192, s[48:49] nt
	v_add_u32_e32 v214, 0x100, v192
	global_load_dwordx4 v[246:249], v214, s[48:49] nt
	v_add_u32_e32 v128, 0x80, v128
	v_ashrrev_i32_e32 v129, 31, v128
	v_add_u32_e32 v226, 0x8000, v192
	v_add_u32_e32 v216, 0x18100, v192
	v_lshl_add_u64 v[128:129], v[128:129], 2, s[22:23]
	v_add_u32_e32 v224, 0x8100, v192
	v_add_u32_e32 v222, 0x10000, v192
	v_add_u32_e32 v220, 0x10100, v192
	v_add_u32_e32 v218, 0x18000, v192
	v_add_u32_e32 v212, 0x40000, v192
	v_add_u32_e32 v210, 0x40100, v192
	v_add_u32_e32 v208, 0x48000, v192
	v_add_u32_e32 v206, 0x48100, v192
	v_add_u32_e32 v204, 0x50000, v192
	v_add_u32_e32 v202, 0x50100, v192
	v_add_u32_e32 v200, 0x58000, v192
	v_add_u32_e32 v198, 0x58100, v192
	global_load_dwordx4 v[180:183], v226, s[48:49] nt
	global_load_dwordx4 v[176:179], v224, s[48:49] nt
	global_load_dwordx4 v[172:175], v222, s[48:49] nt
	global_load_dwordx4 v[168:171], v220, s[48:49] nt
	global_load_dwordx4 v[164:167], v218, s[48:49] nt
	global_load_dwordx4 v[160:163], v216, s[48:49] nt
	global_load_dwordx4 v[156:159], v212, s[48:49] nt
	global_load_dwordx4 v[152:155], v210, s[48:49] nt
	global_load_dwordx4 v[148:151], v208, s[48:49] nt
	global_load_dwordx4 v[144:147], v206, s[48:49] nt
	global_load_dwordx4 v[140:143], v204, s[48:49] nt
	global_load_dwordx4 v[136:139], v202, s[48:49] nt
	global_load_dwordx4 v[132:135], v200, s[48:49] nt
	global_load_dword v201, v[128:129], off
	s_nop 0
	global_load_dwordx4 v[128:131], v198, s[48:49] nt
	v_or_b32_e32 v203, v239, v241
	v_lshlrev_b32_e32 v203, 2, v203
	v_add_u32_e32 v209, s54, v199
	v_cmp_gt_u32_e32 vcc, 16, v199
	v_lshl_add_u32 v199, v209, 4, s60
	s_waitcnt vmcnt(0)
	ds_bpermute_b32 v228, v203, v205
	v_lshlrev_b32_e32 v252, 16, v244
	v_and_b32_e32 v253, 0xffff0000, v244
	v_lshlrev_b32_e32 v244, 16, v245
	v_and_b32_e32 v245, 0xffff0000, v245
	v_lshlrev_b32_e32 v250, 16, v242
	v_and_b32_e32 v251, 0xffff0000, v242
	v_lshlrev_b32_e32 v242, 16, v243
	v_and_b32_e32 v243, 0xffff0000, v243
	v_lshlrev_b32_e32 v232, 16, v246
	v_and_b32_e32 v233, 0xffff0000, v246
	v_lshlrev_b32_e32 v234, 16, v248
	v_and_b32_e32 v235, 0xffff0000, v248
	s_waitcnt lgkmcnt(0)
	v_pk_fma_f32 v[122:123], v[228:229], v[244:245], v[122:123] op_sel_hi:[0,1,1]
	v_pk_fma_f32 v[120:121], v[228:229], v[252:253], v[120:121] op_sel_hi:[0,1,1]
	v_lshlrev_b32_e32 v246, 16, v247
	v_and_b32_e32 v247, 0xffff0000, v247
	v_pk_fma_f32 v[126:127], v[228:229], v[242:243], v[126:127] op_sel_hi:[0,1,1]
	v_pk_fma_f32 v[124:125], v[228:229], v[250:251], v[124:125] op_sel_hi:[0,1,1]
	v_pk_fma_f32 v[116:117], v[228:229], v[232:233], v[116:117] op_sel_hi:[0,1,1]
	v_pk_fma_f32 v[112:113], v[228:229], v[234:235], v[112:113] op_sel_hi:[0,1,1]
	v_pk_mul_f32 v[232:233], v[120:121], v[120:121]
	v_pk_mul_f32 v[234:235], v[122:123], v[122:123]
	v_lshlrev_b32_e32 v248, 16, v249
	v_and_b32_e32 v249, 0xffff0000, v249
	v_pk_fma_f32 v[118:119], v[228:229], v[246:247], v[118:119] op_sel_hi:[0,1,1]
	v_pk_fma_f32 v[234:235], v[126:127], v[126:127], v[234:235]
	v_pk_fma_f32 v[232:233], v[124:125], v[124:125], v[232:233]
	v_pk_fma_f32 v[114:115], v[228:229], v[248:249], v[114:115] op_sel_hi:[0,1,1]
	v_pk_fma_f32 v[232:233], v[116:117], v[116:117], v[232:233]
	v_pk_fma_f32 v[234:235], v[118:119], v[118:119], v[234:235]
	v_pk_fma_f32 v[232:233], v[112:113], v[112:113], v[232:233]
	v_pk_fma_f32 v[234:235], v[114:115], v[114:115], v[234:235]
	v_add_f32_e32 v207, v232, v233
	v_add_f32_e32 v211, v234, v235
	v_add_f32_e32 v207, v207, v211
	v_mov_b32_e32 v211, v207
	s_nop 1
	v_permlane16_swap_b32_e32 v207, v211
	ds_bpermute_b32 v232, v203, v205 offset:64
	ds_bpermute_b32 v230, v203, v205 offset:128
	ds_bpermute_b32 v228, v203, v205 offset:192
	s_waitcnt lgkmcnt(3)
	v_add_f32_e32 v205, v207, v211
	v_mov_b32_e32 v207, v205
	s_nop 1
	v_permlane32_swap_b32_e32 v205, v207
	s_and_saveexec_b64 s[34:35], vcc
	s_cbranch_execz .LBB0_1147
	s_waitcnt lgkmcnt(0)
	v_add_f32_e32 v205, v205, v207
	ds_write_b32 v199, v205
.LBB0_1147:
	s_or_b64 exec, exec, s[34:35]
	v_lshlrev_b32_e32 v234, 16, v180
	v_and_b32_e32 v235, 0xffff0000, v180
	v_lshlrev_b32_e32 v180, 16, v181
	v_and_b32_e32 v181, 0xffff0000, v181
	s_waitcnt lgkmcnt(3)
	v_pk_fma_f32 v[110:111], v[232:233], v[180:181], v[110:111] op_sel_hi:[0,1,1]
	v_lshlrev_b32_e32 v180, 16, v182
	v_and_b32_e32 v181, 0xffff0000, v182
	v_lshlrev_b32_e32 v182, 16, v183
	v_and_b32_e32 v183, 0xffff0000, v183
	v_pk_fma_f32 v[104:105], v[232:233], v[180:181], v[104:105] op_sel_hi:[0,1,1]
	v_lshlrev_b32_e32 v180, 16, v176
	v_and_b32_e32 v181, 0xffff0000, v176
	v_lshlrev_b32_e32 v176, 16, v177
	v_and_b32_e32 v177, 0xffff0000, v177
	v_pk_fma_f32 v[106:107], v[232:233], v[182:183], v[106:107] op_sel_hi:[0,1,1]
	v_pk_fma_f32 v[102:103], v[232:233], v[176:177], v[102:103] op_sel_hi:[0,1,1]
	v_lshlrev_b32_e32 v176, 16, v178
	v_and_b32_e32 v177, 0xffff0000, v178
	v_lshlrev_b32_e32 v178, 16, v179
	v_and_b32_e32 v179, 0xffff0000, v179
	v_pk_fma_f32 v[108:109], v[232:233], v[234:235], v[108:109] op_sel_hi:[0,1,1]
	v_pk_fma_f32 v[98:99], v[232:233], v[178:179], v[98:99] op_sel_hi:[0,1,1]
	v_pk_fma_f32 v[96:97], v[232:233], v[176:177], v[96:97] op_sel_hi:[0,1,1]
	v_pk_mul_f32 v[176:177], v[104:105], v[104:105]
	v_pk_mul_f32 v[178:179], v[106:107], v[106:107]
	v_pk_fma_f32 v[100:101], v[232:233], v[180:181], v[100:101] op_sel_hi:[0,1,1]
	v_pk_fma_f32 v[178:179], v[110:111], v[110:111], v[178:179]
	v_pk_fma_f32 v[176:177], v[108:109], v[108:109], v[176:177]
	v_pk_fma_f32 v[178:179], v[102:103], v[102:103], v[178:179]
	v_pk_fma_f32 v[176:177], v[100:101], v[100:101], v[176:177]
	v_pk_fma_f32 v[178:179], v[98:99], v[98:99], v[178:179]
	v_pk_fma_f32 v[176:177], v[96:97], v[96:97], v[176:177]
	s_nop 0
	v_add_f32_e32 v176, v176, v177
	v_add_f32_e32 v177, v178, v179
	v_add_f32_e32 v176, v176, v177
	v_mov_b32_e32 v177, v176
	s_nop 1
	v_permlane16_swap_b32_e32 v176, v177
	s_waitcnt lgkmcnt(0)
	v_add_f32_e32 v176, v176, v177
	v_mov_b32_e32 v177, v176
	s_nop 1
	v_permlane32_swap_b32_e32 v176, v177
	s_and_saveexec_b64 s[34:35], vcc
	s_cbranch_execz .LBB0_1149
	s_waitcnt lgkmcnt(0)
	v_add_f32_e32 v176, v176, v177
	ds_write_b32 v199, v176 offset:256
.LBB0_1149:
	s_or_b64 exec, exec, s[34:35]
	v_lshlrev_b32_e32 v176, 16, v172
	s_waitcnt lgkmcnt(0)
	v_and_b32_e32 v177, 0xffff0000, v172
	v_lshlrev_b32_e32 v172, 16, v173
	v_and_b32_e32 v173, 0xffff0000, v173
	v_pk_fma_f32 v[94:95], v[230:231], v[172:173], v[94:95] op_sel_hi:[0,1,1]
	v_lshlrev_b32_e32 v172, 16, v174
	v_and_b32_e32 v173, 0xffff0000, v174
	v_lshlrev_b32_e32 v174, 16, v175
	v_and_b32_e32 v175, 0xffff0000, v175
	v_pk_fma_f32 v[88:89], v[230:231], v[172:173], v[88:89] op_sel_hi:[0,1,1]
	v_lshlrev_b32_e32 v172, 16, v168
	v_and_b32_e32 v173, 0xffff0000, v168
	v_lshlrev_b32_e32 v168, 16, v169
	v_and_b32_e32 v169, 0xffff0000, v169
	v_pk_fma_f32 v[90:91], v[230:231], v[174:175], v[90:91] op_sel_hi:[0,1,1]
	v_pk_fma_f32 v[86:87], v[230:231], v[168:169], v[86:87] op_sel_hi:[0,1,1]
	v_lshlrev_b32_e32 v168, 16, v170
	v_and_b32_e32 v169, 0xffff0000, v170
	v_lshlrev_b32_e32 v170, 16, v171
	v_and_b32_e32 v171, 0xffff0000, v171
	v_pk_fma_f32 v[92:93], v[230:231], v[176:177], v[92:93] op_sel_hi:[0,1,1]
	v_pk_fma_f32 v[82:83], v[230:231], v[170:171], v[82:83] op_sel_hi:[0,1,1]
	v_pk_fma_f32 v[80:81], v[230:231], v[168:169], v[80:81] op_sel_hi:[0,1,1]
	v_pk_mul_f32 v[168:169], v[88:89], v[88:89]
	v_pk_mul_f32 v[170:171], v[90:91], v[90:91]
	v_pk_fma_f32 v[84:85], v[230:231], v[172:173], v[84:85] op_sel_hi:[0,1,1]
	v_pk_fma_f32 v[170:171], v[94:95], v[94:95], v[170:171]
	v_pk_fma_f32 v[168:169], v[92:93], v[92:93], v[168:169]
	v_pk_fma_f32 v[170:171], v[86:87], v[86:87], v[170:171]
	v_pk_fma_f32 v[168:169], v[84:85], v[84:85], v[168:169]
	v_pk_fma_f32 v[170:171], v[82:83], v[82:83], v[170:171]
	v_pk_fma_f32 v[168:169], v[80:81], v[80:81], v[168:169]
	s_nop 0
	v_add_f32_e32 v168, v168, v169
	v_add_f32_e32 v169, v170, v171
	v_add_f32_e32 v168, v168, v169
	v_mov_b32_e32 v169, v168
	s_nop 1
	v_permlane16_swap_b32_e32 v168, v169
	s_waitcnt lgkmcnt(0)
	v_add_f32_e32 v168, v168, v169
	v_mov_b32_e32 v169, v168
	s_nop 1
	v_permlane32_swap_b32_e32 v168, v169
	s_and_saveexec_b64 s[34:35], vcc
	s_cbranch_execz .LBB0_1151
	s_waitcnt lgkmcnt(0)
	v_add_f32_e32 v168, v168, v169
	ds_write_b32 v199, v168 offset:512
.LBB0_1151:
	s_or_b64 exec, exec, s[34:35]
	v_lshlrev_b32_e32 v168, 16, v164
	s_waitcnt lgkmcnt(0)
	v_and_b32_e32 v169, 0xffff0000, v164
	v_lshlrev_b32_e32 v164, 16, v165
	v_and_b32_e32 v165, 0xffff0000, v165
	v_pk_fma_f32 v[78:79], v[228:229], v[164:165], v[78:79] op_sel_hi:[0,1,1]
	v_lshlrev_b32_e32 v164, 16, v166
	v_and_b32_e32 v165, 0xffff0000, v166
	v_lshlrev_b32_e32 v166, 16, v167
	v_and_b32_e32 v167, 0xffff0000, v167
	v_pk_fma_f32 v[72:73], v[228:229], v[164:165], v[72:73] op_sel_hi:[0,1,1]
	v_lshlrev_b32_e32 v164, 16, v160
	v_and_b32_e32 v165, 0xffff0000, v160
	v_lshlrev_b32_e32 v160, 16, v161
	v_and_b32_e32 v161, 0xffff0000, v161
	v_pk_fma_f32 v[74:75], v[228:229], v[166:167], v[74:75] op_sel_hi:[0,1,1]
	v_pk_fma_f32 v[70:71], v[228:229], v[160:161], v[70:71] op_sel_hi:[0,1,1]
	v_lshlrev_b32_e32 v160, 16, v162
	v_and_b32_e32 v161, 0xffff0000, v162
	v_lshlrev_b32_e32 v162, 16, v163
	v_and_b32_e32 v163, 0xffff0000, v163
	v_pk_fma_f32 v[76:77], v[228:229], v[168:169], v[76:77] op_sel_hi:[0,1,1]
	v_pk_fma_f32 v[66:67], v[228:229], v[162:163], v[66:67] op_sel_hi:[0,1,1]
	v_pk_fma_f32 v[64:65], v[228:229], v[160:161], v[64:65] op_sel_hi:[0,1,1]
	v_pk_mul_f32 v[160:161], v[72:73], v[72:73]
	v_pk_mul_f32 v[162:163], v[74:75], v[74:75]
	v_pk_fma_f32 v[68:69], v[228:229], v[164:165], v[68:69] op_sel_hi:[0,1,1]
	v_pk_fma_f32 v[162:163], v[78:79], v[78:79], v[162:163]
	v_pk_fma_f32 v[160:161], v[76:77], v[76:77], v[160:161]
	v_pk_fma_f32 v[162:163], v[70:71], v[70:71], v[162:163]
	v_pk_fma_f32 v[160:161], v[68:69], v[68:69], v[160:161]
	v_pk_fma_f32 v[162:163], v[66:67], v[66:67], v[162:163]
	v_pk_fma_f32 v[160:161], v[64:65], v[64:65], v[160:161]
	s_nop 0
	v_add_f32_e32 v160, v160, v161
	v_add_f32_e32 v161, v162, v163
	v_add_f32_e32 v160, v160, v161
	v_mov_b32_e32 v161, v160
	s_nop 1
	v_permlane16_swap_b32_e32 v160, v161
	s_waitcnt lgkmcnt(0)
	v_add_f32_e32 v160, v160, v161
	v_mov_b32_e32 v161, v160
	s_nop 1
	v_permlane32_swap_b32_e32 v160, v161
	s_and_saveexec_b64 s[34:35], vcc
	s_cbranch_execz .LBB0_1153
	s_waitcnt lgkmcnt(0)
	v_add_f32_e32 v160, v160, v161
	ds_write_b32 v199, v160 offset:768
.LBB0_1153:
	s_or_b64 exec, exec, s[34:35]
	v_mov_b32_e32 v215, v193
	v_mov_b32_e32 v227, v193
	v_mov_b32_e32 v225, v193
	v_mov_b32_e32 v223, v193
	v_mov_b32_e32 v221, v193
	v_mov_b32_e32 v219, v193
	s_waitcnt lgkmcnt(0)
	v_lshl_add_u64 v[160:161], s[48:49], 0, v[192:193]
	v_lshl_add_u64 v[162:163], s[48:49], 0, v[214:215]
	v_lshl_add_u64 v[164:165], s[48:49], 0, v[226:227]
	v_lshl_add_u64 v[166:167], s[48:49], 0, v[224:225]
	v_lshl_add_u64 v[168:169], s[48:49], 0, v[222:223]
	v_lshl_add_u64 v[170:171], s[48:49], 0, v[220:221]
	v_lshl_add_u64 v[172:173], s[48:49], 0, v[218:219]
	v_cvt_pk_bf16_f32 v124, v124, v125
	v_cvt_pk_bf16_f32 v125, v126, v127
	v_cvt_pk_bf16_f32 v126, v120, v121
	v_cvt_pk_bf16_f32 v127, v122, v123
	global_store_dwordx4 v[160:161], v[124:127], off
	v_cvt_pk_bf16_f32 v116, v116, v117
	v_cvt_pk_bf16_f32 v117, v118, v119
	v_cvt_pk_bf16_f32 v118, v112, v113
	v_cvt_pk_bf16_f32 v119, v114, v115
	global_store_dwordx4 v[162:163], v[116:119], off
	v_cvt_pk_bf16_f32 v108, v108, v109
	v_cvt_pk_bf16_f32 v109, v110, v111
	v_cvt_pk_bf16_f32 v110, v104, v105
	v_cvt_pk_bf16_f32 v111, v106, v107
	global_store_dwordx4 v[164:165], v[108:111], off
	v_cvt_pk_bf16_f32 v100, v100, v101
	v_cvt_pk_bf16_f32 v101, v102, v103
	v_cvt_pk_bf16_f32 v102, v96, v97
	v_cvt_pk_bf16_f32 v103, v98, v99
	global_store_dwordx4 v[166:167], v[100:103], off
	v_cvt_pk_bf16_f32 v92, v92, v93
	v_cvt_pk_bf16_f32 v93, v94, v95
	v_cvt_pk_bf16_f32 v94, v88, v89
	v_cvt_pk_bf16_f32 v95, v90, v91
	global_store_dwordx4 v[168:169], v[92:95], off
	v_cvt_pk_bf16_f32 v84, v84, v85
	v_cvt_pk_bf16_f32 v85, v86, v87
	v_cvt_pk_bf16_f32 v86, v80, v81
	v_cvt_pk_bf16_f32 v87, v82, v83
	global_store_dwordx4 v[170:171], v[84:87], off
	v_cvt_pk_bf16_f32 v76, v76, v77
	v_cvt_pk_bf16_f32 v77, v78, v79
	v_cvt_pk_bf16_f32 v78, v72, v73
	v_cvt_pk_bf16_f32 v79, v74, v75
	global_store_dwordx4 v[172:173], v[76:79], off
	v_cvt_pk_bf16_f32 v68, v68, v69
	v_cvt_pk_bf16_f32 v69, v70, v71
	v_cvt_pk_bf16_f32 v70, v64, v65
	ds_bpermute_b32 v64, v203, v201
	v_mov_b32_e32 v217, v193
	v_lshl_add_u64 v[174:175], s[48:49], 0, v[216:217]
	v_cvt_pk_bf16_f32 v71, v66, v67
	global_store_dwordx4 v[174:175], v[68:71], off
	v_lshlrev_b32_e32 v66, 16, v156
	v_and_b32_e32 v67, 0xffff0000, v156
	v_lshlrev_b32_e32 v68, 16, v157
	v_and_b32_e32 v69, 0xffff0000, v157
	s_waitcnt lgkmcnt(0)
	v_pk_fma_f32 v[62:63], v[64:65], v[68:69], v[62:63] op_sel_hi:[0,1,1]
	v_pk_fma_f32 v[60:61], v[64:65], v[66:67], v[60:61] op_sel_hi:[0,1,1]
	v_lshlrev_b32_e32 v66, 16, v158
	v_and_b32_e32 v67, 0xffff0000, v158
	v_lshlrev_b32_e32 v68, 16, v159
	v_and_b32_e32 v69, 0xffff0000, v159
	v_pk_fma_f32 v[58:59], v[64:65], v[68:69], v[58:59] op_sel_hi:[0,1,1]
	v_pk_fma_f32 v[56:57], v[64:65], v[66:67], v[56:57] op_sel_hi:[0,1,1]
	v_lshlrev_b32_e32 v66, 16, v152
	v_and_b32_e32 v67, 0xffff0000, v152
	v_lshlrev_b32_e32 v68, 16, v153
	v_and_b32_e32 v69, 0xffff0000, v153
	v_pk_fma_f32 v[54:55], v[64:65], v[68:69], v[54:55] op_sel_hi:[0,1,1]
	v_pk_fma_f32 v[52:53], v[64:65], v[66:67], v[52:53] op_sel_hi:[0,1,1]
	v_lshlrev_b32_e32 v66, 16, v154
	v_and_b32_e32 v67, 0xffff0000, v154
	v_lshlrev_b32_e32 v68, 16, v155
	v_and_b32_e32 v69, 0xffff0000, v155
	v_pk_fma_f32 v[50:51], v[64:65], v[68:69], v[50:51] op_sel_hi:[0,1,1]
	v_pk_fma_f32 v[48:49], v[64:65], v[66:67], v[48:49] op_sel_hi:[0,1,1]
	v_pk_mul_f32 v[64:65], v[56:57], v[56:57]
	v_pk_mul_f32 v[66:67], v[58:59], v[58:59]
	v_pk_fma_f32 v[64:65], v[60:61], v[60:61], v[64:65]
	v_pk_fma_f32 v[66:67], v[62:63], v[62:63], v[66:67]
	v_pk_fma_f32 v[64:65], v[52:53], v[52:53], v[64:65]
	v_pk_fma_f32 v[66:67], v[54:55], v[54:55], v[66:67]
	v_pk_fma_f32 v[64:65], v[48:49], v[48:49], v[64:65]
	v_pk_fma_f32 v[66:67], v[50:51], v[50:51], v[66:67]
	v_add_f32_e32 v64, v64, v65
	v_add_f32_e32 v65, v66, v67
	v_add_f32_e32 v65, v64, v65
	v_mov_b32_e32 v67, v65
	s_nop 1
	v_permlane16_swap_b32_e32 v65, v67
	v_or_b32_e32 v176, 64, v203
	v_or_b32_e32 v177, 0x80, v203
	v_or_b32_e32 v178, 0xc0, v203
	ds_bpermute_b32 v68, v176, v201
	s_waitcnt lgkmcnt(1)
	v_add_f32_e32 v65, v65, v67
	ds_bpermute_b32 v66, v177, v201
	ds_bpermute_b32 v64, v178, v201
	v_mov_b32_e32 v67, v65
	s_nop 1
	v_permlane32_swap_b32_e32 v65, v67
	s_and_saveexec_b64 s[34:35], vcc
	s_cbranch_execz .LBB0_1155
	s_waitcnt lgkmcnt(0)
	v_add_f32_e32 v65, v65, v67
	ds_write_b32 v199, v65 offset:2048
.LBB0_1155:
	s_or_b64 exec, exec, s[34:35]
	v_lshlrev_b32_e32 v70, 16, v148
	v_and_b32_e32 v71, 0xffff0000, v148
	v_lshlrev_b32_e32 v72, 16, v149
	v_and_b32_e32 v73, 0xffff0000, v149
	s_waitcnt lgkmcnt(3)
	v_pk_fma_f32 v[46:47], v[68:69], v[72:73], v[46:47] op_sel_hi:[0,1,1]
	v_pk_fma_f32 v[44:45], v[68:69], v[70:71], v[44:45] op_sel_hi:[0,1,1]
	v_lshlrev_b32_e32 v70, 16, v150
	v_and_b32_e32 v71, 0xffff0000, v150
	v_lshlrev_b32_e32 v72, 16, v151
	v_and_b32_e32 v73, 0xffff0000, v151
	v_pk_fma_f32 v[42:43], v[68:69], v[72:73], v[42:43] op_sel_hi:[0,1,1]
	v_pk_fma_f32 v[40:41], v[68:69], v[70:71], v[40:41] op_sel_hi:[0,1,1]
	v_lshlrev_b32_e32 v70, 16, v144
	v_and_b32_e32 v71, 0xffff0000, v144
	v_lshlrev_b32_e32 v72, 16, v145
	v_and_b32_e32 v73, 0xffff0000, v145
	v_pk_fma_f32 v[38:39], v[68:69], v[72:73], v[38:39] op_sel_hi:[0,1,1]
	v_pk_fma_f32 v[36:37], v[68:69], v[70:71], v[36:37] op_sel_hi:[0,1,1]
	v_lshlrev_b32_e32 v70, 16, v146
	v_and_b32_e32 v71, 0xffff0000, v146
	v_lshlrev_b32_e32 v72, 16, v147
	v_and_b32_e32 v73, 0xffff0000, v147
	v_pk_fma_f32 v[34:35], v[68:69], v[72:73], v[34:35] op_sel_hi:[0,1,1]
	v_pk_fma_f32 v[32:33], v[68:69], v[70:71], v[32:33] op_sel_hi:[0,1,1]
	v_pk_mul_f32 v[68:69], v[40:41], v[40:41]
	v_pk_mul_f32 v[70:71], v[42:43], v[42:43]
	v_pk_fma_f32 v[68:69], v[44:45], v[44:45], v[68:69]
	v_pk_fma_f32 v[70:71], v[46:47], v[46:47], v[70:71]
	v_pk_fma_f32 v[68:69], v[36:37], v[36:37], v[68:69]
	v_pk_fma_f32 v[70:71], v[38:39], v[38:39], v[70:71]
	v_pk_fma_f32 v[68:69], v[32:33], v[32:33], v[68:69]
	v_pk_fma_f32 v[70:71], v[34:35], v[34:35], v[70:71]
	v_add_f32_e32 v65, v68, v69
	s_waitcnt lgkmcnt(0)
	v_add_f32_e32 v67, v70, v71
	v_add_f32_e32 v65, v65, v67
	v_mov_b32_e32 v67, v65
	s_nop 1
	v_permlane16_swap_b32_e32 v65, v67
	s_waitcnt lgkmcnt(0)
	v_add_f32_e32 v65, v65, v67
	v_mov_b32_e32 v67, v65
	s_nop 1
	v_permlane32_swap_b32_e32 v65, v67
	s_and_saveexec_b64 s[34:35], vcc
	s_cbranch_execz .LBB0_1157
	s_waitcnt lgkmcnt(0)
	v_add_f32_e32 v65, v65, v67
	ds_write_b32 v199, v65 offset:2304
.LBB0_1157:
	s_or_b64 exec, exec, s[34:35]
	v_lshlrev_b32_e32 v68, 16, v140
	v_and_b32_e32 v69, 0xffff0000, v140
	v_lshlrev_b32_e32 v70, 16, v141
	v_and_b32_e32 v71, 0xffff0000, v141
	s_waitcnt lgkmcnt(0)
	v_pk_fma_f32 v[30:31], v[66:67], v[70:71], v[30:31] op_sel_hi:[0,1,1]
	v_pk_fma_f32 v[28:29], v[66:67], v[68:69], v[28:29] op_sel_hi:[0,1,1]
	v_lshlrev_b32_e32 v68, 16, v142
	v_and_b32_e32 v69, 0xffff0000, v142
	v_lshlrev_b32_e32 v70, 16, v143
	v_and_b32_e32 v71, 0xffff0000, v143
	v_pk_fma_f32 v[26:27], v[66:67], v[70:71], v[26:27] op_sel_hi:[0,1,1]
	v_pk_fma_f32 v[24:25], v[66:67], v[68:69], v[24:25] op_sel_hi:[0,1,1]
	v_lshlrev_b32_e32 v68, 16, v136
	v_and_b32_e32 v69, 0xffff0000, v136
	v_lshlrev_b32_e32 v70, 16, v137
	v_and_b32_e32 v71, 0xffff0000, v137
	v_pk_fma_f32 v[22:23], v[66:67], v[70:71], v[22:23] op_sel_hi:[0,1,1]
	v_pk_fma_f32 v[20:21], v[66:67], v[68:69], v[20:21] op_sel_hi:[0,1,1]
	v_lshlrev_b32_e32 v68, 16, v138
	v_and_b32_e32 v69, 0xffff0000, v138
	v_lshlrev_b32_e32 v70, 16, v139
	v_and_b32_e32 v71, 0xffff0000, v139
	v_pk_fma_f32 v[18:19], v[66:67], v[70:71], v[18:19] op_sel_hi:[0,1,1]
	v_pk_fma_f32 v[16:17], v[66:67], v[68:69], v[16:17] op_sel_hi:[0,1,1]
	v_pk_mul_f32 v[66:67], v[24:25], v[24:25]
	v_pk_mul_f32 v[68:69], v[26:27], v[26:27]
	v_pk_fma_f32 v[66:67], v[28:29], v[28:29], v[66:67]
	v_pk_fma_f32 v[68:69], v[30:31], v[30:31], v[68:69]
	v_pk_fma_f32 v[66:67], v[20:21], v[20:21], v[66:67]
	v_pk_fma_f32 v[68:69], v[22:23], v[22:23], v[68:69]
	v_pk_fma_f32 v[66:67], v[16:17], v[16:17], v[66:67]
	v_pk_fma_f32 v[68:69], v[18:19], v[18:19], v[68:69]
	v_add_f32_e32 v65, v66, v67
	v_add_f32_e32 v66, v68, v69
	v_add_f32_e32 v65, v65, v66
	v_mov_b32_e32 v66, v65
	s_nop 1
	v_permlane16_swap_b32_e32 v65, v66
	s_waitcnt lgkmcnt(0)
	v_add_f32_e32 v65, v65, v66
	v_mov_b32_e32 v66, v65
	s_nop 1
	v_permlane32_swap_b32_e32 v65, v66
	s_and_saveexec_b64 s[34:35], vcc
	s_cbranch_execz .LBB0_1159
	s_waitcnt lgkmcnt(0)
	v_add_f32_e32 v65, v65, v66
	ds_write_b32 v199, v65 offset:2560
.LBB0_1159:
	s_or_b64 exec, exec, s[34:35]
	s_waitcnt lgkmcnt(0)
	v_lshlrev_b32_e32 v66, 16, v132
	v_and_b32_e32 v67, 0xffff0000, v132
	v_lshlrev_b32_e32 v68, 16, v133
	v_and_b32_e32 v69, 0xffff0000, v133
	v_pk_fma_f32 v[14:15], v[64:65], v[68:69], v[14:15] op_sel_hi:[0,1,1]
	v_pk_fma_f32 v[12:13], v[64:65], v[66:67], v[12:13] op_sel_hi:[0,1,1]
	v_lshlrev_b32_e32 v66, 16, v134
	v_and_b32_e32 v67, 0xffff0000, v134
	v_lshlrev_b32_e32 v68, 16, v135
	v_and_b32_e32 v69, 0xffff0000, v135
	v_pk_fma_f32 v[10:11], v[64:65], v[68:69], v[10:11] op_sel_hi:[0,1,1]
	v_pk_fma_f32 v[8:9], v[64:65], v[66:67], v[8:9] op_sel_hi:[0,1,1]
	v_lshlrev_b32_e32 v66, 16, v128
	v_and_b32_e32 v67, 0xffff0000, v128
	v_lshlrev_b32_e32 v68, 16, v129
	v_and_b32_e32 v69, 0xffff0000, v129
	v_pk_fma_f32 v[6:7], v[64:65], v[68:69], v[6:7] op_sel_hi:[0,1,1]
	v_pk_fma_f32 v[4:5], v[64:65], v[66:67], v[4:5] op_sel_hi:[0,1,1]
	v_lshlrev_b32_e32 v66, 16, v130
	v_and_b32_e32 v67, 0xffff0000, v130
	v_lshlrev_b32_e32 v68, 16, v131
	v_and_b32_e32 v69, 0xffff0000, v131
	v_pk_fma_f32 v[2:3], v[64:65], v[68:69], v[2:3] op_sel_hi:[0,1,1]
	v_pk_fma_f32 v[0:1], v[64:65], v[66:67], v[0:1] op_sel_hi:[0,1,1]
	v_pk_mul_f32 v[64:65], v[8:9], v[8:9]
	v_pk_mul_f32 v[66:67], v[10:11], v[10:11]
	v_pk_fma_f32 v[64:65], v[12:13], v[12:13], v[64:65]
	v_pk_fma_f32 v[66:67], v[14:15], v[14:15], v[66:67]
	v_pk_fma_f32 v[64:65], v[4:5], v[4:5], v[64:65]
	v_pk_fma_f32 v[66:67], v[6:7], v[6:7], v[66:67]
	v_pk_fma_f32 v[64:65], v[0:1], v[0:1], v[64:65]
	v_pk_fma_f32 v[66:67], v[2:3], v[2:3], v[66:67]
	v_add_f32_e32 v64, v64, v65
	v_add_f32_e32 v65, v66, v67
	v_add_f32_e32 v64, v64, v65
	v_mov_b32_e32 v65, v64
	s_nop 1
	v_permlane16_swap_b32_e32 v64, v65
	s_waitcnt lgkmcnt(0)
	v_add_f32_e32 v64, v64, v65
	v_mov_b32_e32 v65, v64
	s_nop 1
	v_permlane32_swap_b32_e32 v64, v65
	s_and_saveexec_b64 s[34:35], vcc
	s_cbranch_execz .LBB0_1161
	s_waitcnt lgkmcnt(0)
	v_add_f32_e32 v64, v64, v65
	ds_write_b32 v199, v64 offset:2816
